# FFN-in epilogue: hoist the 8 per-row sum-of-squares loads to the epilogue top (counted vmcnt) on top of v1
# baseline (speedup 1.0000x reference)
.LBB0_934:
	s_mul_hi_i32 s0, s31, 0x78787879
	s_lshr_b32 s1, s0, 31
	s_ashr_i32 s0, s0, 3
	s_add_i32 s0, s0, s1
	s_mul_i32 s1, s0, 17
	v_mov_b32_e32 v136, v200
	v_mov_b32_e32 v203, v1
	s_sub_i32 s12, s31, s1
	s_mul_i32 s31, s12, 0xfe
	v_lshlrev_b32_e32 v130, 2, v203
	v_readlane_b32 s1, v254, 58
	s_add_i32 s31, s31, -2
	v_mov_b32_e32 v144, 0xfff
	v_add_u32_e32 v199, s1, v130
	v_add_u32_e32 v190, s31, v199
	v_lshl_add_u32 v130, v136, 6, v130
	s_lshl_b32 s1, s0, 12
	v_xor_b32_e32 v138, 64, v130
	v_xor_b32_e32 v137, 0x80, v130
	v_med3_i32 v130, v190, 0, v144
	v_or_b32_e32 v130, s1, v130
	v_lshlrev_b32_e32 v134, 2, v136
	v_ashrrev_i32_e32 v131, 31, v130
	v_readlane_b32 s24, v254, 45
	v_ashrrev_i32_e32 v135, 31, v134
	v_lshlrev_b64 v[130:131], 6, v[130:131]
	v_readlane_b32 s25, v254, 46
	s_nop 1
	v_lshl_add_u64 v[132:133], s[24:25], 0, v[130:131]
	v_lshlrev_b64 v[130:131], 2, v[134:135]
	v_lshl_add_u64 v[132:133], v[132:133], 0, v[130:131]
	global_load_dwordx4 v[146:149], v[132:133], off
	v_or_b32_e32 v192, 1, v190
	v_med3_i32 v192, v192, 0, v144
	v_or_b32_e32 v192, s1, v192
	v_ashrrev_i32_e32 v193, 31, v192
	v_lshlrev_b64 v[192:193], 6, v[192:193]
	v_lshl_add_u64 v[192:193], s[24:25], 0, v[192:193]
	v_lshl_add_u64 v[192:193], v[192:193], 0, v[130:131]
	global_load_dwordx4 v[150:153], v[192:193], off
	v_max_i32_e32 v192, -2, v190
	v_add_u32_e32 v192, 2, v192
	v_min_u32_e32 v192, 0xfff, v192
	v_or_b32_e32 v192, s1, v192
	v_ashrrev_i32_e32 v193, 31, v192
	v_lshlrev_b64 v[192:193], 6, v[192:193]
	v_lshl_add_u64 v[192:193], s[24:25], 0, v[192:193]
	v_lshl_add_u64 v[192:193], v[192:193], 0, v[130:131]
	global_load_dwordx4 v[154:157], v[192:193], off
	v_max_i32_e32 v192, -3, v190
	v_add_u32_e32 v192, 3, v192
	v_min_u32_e32 v192, 0xfff, v192
	v_or_b32_e32 v192, s1, v192
	v_ashrrev_i32_e32 v193, 31, v192
	v_lshlrev_b64 v[192:193], 6, v[192:193]
	v_lshl_add_u64 v[192:193], s[24:25], 0, v[192:193]
	v_lshl_add_u64 v[192:193], v[192:193], 0, v[130:131]
	global_load_dwordx4 v[158:161], v[192:193], off
	v_add_u32_e32 v192, 0x80, v190
	v_med3_i32 v192, v192, 0, v144
	v_or_b32_e32 v192, s1, v192
	v_ashrrev_i32_e32 v193, 31, v192
	v_lshlrev_b64 v[192:193], 6, v[192:193]
	v_lshl_add_u64 v[192:193], s[24:25], 0, v[192:193]
	v_lshl_add_u64 v[192:193], v[192:193], 0, v[130:131]
	global_load_dwordx4 v[162:165], v[192:193], off
	v_add_u32_e32 v192, 0x81, v190
	v_med3_i32 v192, v192, 0, v144
	v_or_b32_e32 v192, s1, v192
	v_ashrrev_i32_e32 v193, 31, v192
	v_lshlrev_b64 v[192:193], 6, v[192:193]
	v_lshl_add_u64 v[192:193], s[24:25], 0, v[192:193]
	v_lshl_add_u64 v[192:193], v[192:193], 0, v[130:131]
	global_load_dwordx4 v[166:169], v[192:193], off
	v_add_u32_e32 v192, 0x82, v190
	v_med3_i32 v192, v192, 0, v144
	v_or_b32_e32 v192, s1, v192
	v_ashrrev_i32_e32 v193, 31, v192
	v_lshlrev_b64 v[192:193], 6, v[192:193]
	v_lshl_add_u64 v[192:193], s[24:25], 0, v[192:193]
	v_lshl_add_u64 v[192:193], v[192:193], 0, v[130:131]
	global_load_dwordx4 v[170:173], v[192:193], off
	v_add_u32_e32 v192, 0x83, v190
	v_med3_i32 v192, v192, 0, v144
	v_or_b32_e32 v192, s1, v192
	v_ashrrev_i32_e32 v193, 31, v192
	v_lshlrev_b64 v[192:193], 6, v[192:193]
	v_lshl_add_u64 v[192:193], s[24:25], 0, v[192:193]
	v_lshl_add_u64 v[192:193], v[192:193], 0, v[130:131]
	global_load_dwordx4 v[174:177], v[192:193], off
	s_waitcnt vmcnt(7)
	v_mov_b64_e32 v[140:141], v[146:147]
	v_mov_b64_e32 v[142:143], v[148:149]
	v_mov_b32_e32 v132, v141
	v_mov_b32_e32 v133, v142
	v_mov_b32_e32 v141, v143
	v_pk_add_f32 v[132:133], v[132:133], v[140:141]
	s_nop 0
	v_add_f32_e32 v132, v132, v133
	ds_bpermute_b32 v133, v138, v132
	s_waitcnt lgkmcnt(0)
	v_add_f32_e32 v191, v132, v133
	v_or_b32_e32 v132, 1, v190
	v_med3_i32 v132, v132, 0, v144
	v_or_b32_e32 v132, s1, v132
	v_ashrrev_i32_e32 v133, 31, v132
	v_lshlrev_b64 v[132:133], 6, v[132:133]
	v_lshl_add_u64 v[132:133], s[24:25], 0, v[132:133]
	v_lshl_add_u64 v[132:133], v[132:133], 0, v[130:131]
	ds_bpermute_b32 v198, v137, v191
	s_waitcnt vmcnt(6)
	v_mov_b64_e32 v[140:141], v[150:151]
	v_mov_b64_e32 v[142:143], v[152:153]
	v_mov_b32_e32 v132, v141
	v_mov_b32_e32 v133, v142
	v_mov_b32_e32 v141, v143
	v_pk_add_f32 v[132:133], v[132:133], v[140:141]
	s_nop 0
	v_add_f32_e32 v132, v132, v133
	ds_bpermute_b32 v133, v138, v132
	s_waitcnt lgkmcnt(0)
	v_add_f32_e32 v208, v132, v133
	v_max_i32_e32 v132, -2, v190
	v_add_u32_e32 v132, 2, v132
	v_min_u32_e32 v132, 0xfff, v132
	v_or_b32_e32 v132, s1, v132
	v_ashrrev_i32_e32 v133, 31, v132
	v_lshlrev_b64 v[132:133], 6, v[132:133]
	v_lshl_add_u64 v[132:133], s[24:25], 0, v[132:133]
	v_lshl_add_u64 v[132:133], v[132:133], 0, v[130:131]
	ds_bpermute_b32 v209, v137, v208
	s_waitcnt vmcnt(5)
	v_mov_b64_e32 v[140:141], v[154:155]
	v_mov_b64_e32 v[142:143], v[156:157]
	v_mov_b32_e32 v132, v141
	v_mov_b32_e32 v133, v142
	v_mov_b32_e32 v141, v143
	v_pk_add_f32 v[132:133], v[132:133], v[140:141]
	s_nop 0
	v_add_f32_e32 v132, v132, v133
	ds_bpermute_b32 v133, v138, v132
	s_waitcnt lgkmcnt(0)
	v_add_f32_e32 v132, v132, v133
	ds_bpermute_b32 v133, v137, v132
	s_waitcnt lgkmcnt(0)
	v_add_f32_e32 v132, v132, v133
	v_fmamk_f32 v132, v132, 0x3a800000, v243
	v_cmp_gt_f32_e32 vcc, s37, v132
	v_mul_f32_e32 v133, 0x4f800000, v132
	s_nop 0
	v_cndmask_b32_e32 v132, v132, v133, vcc
	v_sqrt_f32_e32 v133, v132
	s_nop 0
	v_add_u32_e32 v135, -1, v133
	v_fma_f32 v139, -v135, v133, v132
	v_cmp_ge_f32_e64 s[44:45], 0, v139
	v_add_u32_e32 v139, 1, v133
	s_nop 0
	v_cndmask_b32_e64 v135, v133, v135, s[44:45]
	v_fma_f32 v133, -v139, v133, v132
	v_cmp_lt_f32_e64 s[44:45], 0, v133
	s_nop 1
	v_cndmask_b32_e64 v133, v135, v139, s[44:45]
	v_mul_f32_e32 v135, 0x37800000, v133
	v_cndmask_b32_e32 v133, v133, v135, vcc
	v_cmp_class_f32_e32 vcc, v132, v241
	s_nop 1
	v_cndmask_b32_e32 v132, v133, v132, vcc
	v_div_scale_f32 v133, s[10:11], v132, v132, 1.0
	v_rcp_f32_e32 v135, v133
	s_nop 0
	v_fma_f32 v139, -v133, v135, 1.0
	v_fmac_f32_e32 v135, v139, v135
	v_div_scale_f32 v139, vcc, 1.0, v132, 1.0
	v_mul_f32_e32 v140, v139, v135
	v_fma_f32 v141, -v133, v140, v139
	v_fmac_f32_e32 v140, v141, v135
	v_fma_f32 v133, -v133, v140, v139
	v_div_fmas_f32 v133, v133, v135, v140
	v_div_fixup_f32 v132, v133, v132, 1.0
	v_pk_mul_f32 v[116:117], v[116:117], v[132:133] op_sel_hi:[1,0]
	v_pk_mul_f32 v[114:115], v[114:115], v[132:133] op_sel_hi:[1,0]
	v_pk_mul_f32 v[44:45], v[44:45], v[132:133] op_sel_hi:[1,0]
	v_pk_mul_f32 v[42:43], v[42:43], v[132:133] op_sel_hi:[1,0]
	v_pk_mul_f32 v[120:121], v[120:121], v[132:133] op_sel_hi:[1,0]
	v_pk_mul_f32 v[118:119], v[118:119], v[132:133] op_sel_hi:[1,0]
	v_pk_mul_f32 v[56:57], v[56:57], v[132:133] op_sel_hi:[1,0]
	v_pk_mul_f32 v[54:55], v[54:55], v[132:133] op_sel_hi:[1,0]
	v_max_i32_e32 v132, -3, v190
	v_add_u32_e32 v132, 3, v132
	v_min_u32_e32 v132, 0xfff, v132
	v_or_b32_e32 v132, s1, v132
	v_ashrrev_i32_e32 v133, 31, v132
	v_lshlrev_b64 v[132:133], 6, v[132:133]
	v_lshl_add_u64 v[132:133], s[24:25], 0, v[132:133]
	v_lshl_add_u64 v[132:133], v[132:133], 0, v[130:131]
	s_waitcnt vmcnt(4)
	v_mov_b64_e32 v[140:141], v[158:159]
	v_mov_b64_e32 v[142:143], v[160:161]
	v_mov_b32_e32 v132, v141
	v_mov_b32_e32 v133, v142
	v_mov_b32_e32 v141, v143
	v_pk_add_f32 v[132:133], v[132:133], v[140:141]
	s_nop 0
	v_add_f32_e32 v132, v132, v133
	ds_bpermute_b32 v133, v138, v132
	s_waitcnt lgkmcnt(0)
	v_add_f32_e32 v132, v132, v133
	ds_bpermute_b32 v133, v137, v132
	s_waitcnt lgkmcnt(0)
	v_add_f32_e32 v132, v132, v133
	v_fmamk_f32 v132, v132, 0x3a800000, v243
	v_cmp_gt_f32_e32 vcc, s37, v132
	v_mul_f32_e32 v133, 0x4f800000, v132
	s_nop 0
	v_cndmask_b32_e32 v132, v132, v133, vcc
	v_sqrt_f32_e32 v133, v132
	s_nop 0
	v_add_u32_e32 v135, -1, v133
	v_fma_f32 v139, -v135, v133, v132
	v_cmp_ge_f32_e64 s[44:45], 0, v139
	v_add_u32_e32 v139, 1, v133
	s_nop 0
	v_cndmask_b32_e64 v135, v133, v135, s[44:45]
	v_fma_f32 v133, -v139, v133, v132
	v_cmp_lt_f32_e64 s[44:45], 0, v133
	s_nop 1
	v_cndmask_b32_e64 v133, v135, v139, s[44:45]
	v_mul_f32_e32 v135, 0x37800000, v133
	v_cndmask_b32_e32 v133, v133, v135, vcc
	v_cmp_class_f32_e32 vcc, v132, v241
	s_nop 1
	v_cndmask_b32_e32 v132, v133, v132, vcc
	v_div_scale_f32 v133, s[10:11], v132, v132, 1.0
	v_rcp_f32_e32 v135, v133
	s_nop 0
	v_fma_f32 v139, -v133, v135, 1.0
	v_fmac_f32_e32 v135, v139, v135
	v_div_scale_f32 v139, vcc, 1.0, v132, 1.0
	v_mul_f32_e32 v140, v139, v135
	v_fma_f32 v141, -v133, v140, v139
	v_fmac_f32_e32 v140, v141, v135
	v_fma_f32 v133, -v133, v140, v139
	v_div_fmas_f32 v133, v133, v135, v140
	v_div_fixup_f32 v132, v133, v132, 1.0
	v_pk_mul_f32 v[124:125], v[124:125], v[132:133] op_sel_hi:[1,0]
	v_pk_mul_f32 v[122:123], v[122:123], v[132:133] op_sel_hi:[1,0]
	v_pk_mul_f32 v[60:61], v[60:61], v[132:133] op_sel_hi:[1,0]
	v_pk_mul_f32 v[58:59], v[58:59], v[132:133] op_sel_hi:[1,0]
	v_pk_mul_f32 v[128:129], v[128:129], v[132:133] op_sel_hi:[1,0]
	v_pk_mul_f32 v[126:127], v[126:127], v[132:133] op_sel_hi:[1,0]
	v_pk_mul_f32 v[64:65], v[64:65], v[132:133] op_sel_hi:[1,0]
	v_pk_mul_f32 v[62:63], v[62:63], v[132:133] op_sel_hi:[1,0]
	v_add_u32_e32 v132, 0x80, v190
	v_med3_i32 v132, v132, 0, v144
	v_or_b32_e32 v132, s1, v132
	v_ashrrev_i32_e32 v133, 31, v132
	v_lshlrev_b64 v[132:133], 6, v[132:133]
	v_lshl_add_u64 v[132:133], s[24:25], 0, v[132:133]
	v_lshl_add_u64 v[132:133], v[132:133], 0, v[130:131]
	s_waitcnt vmcnt(3)
	v_mov_b64_e32 v[140:141], v[162:163]
	v_mov_b64_e32 v[142:143], v[164:165]
	v_mov_b32_e32 v132, v141
	v_mov_b32_e32 v133, v142
	v_mov_b32_e32 v141, v143
	v_pk_add_f32 v[132:133], v[132:133], v[140:141]
	s_nop 0
	v_add_f32_e32 v132, v132, v133
	ds_bpermute_b32 v133, v138, v132
	s_waitcnt lgkmcnt(0)
	v_add_f32_e32 v206, v132, v133
	v_add_u32_e32 v132, 0x81, v190
	v_med3_i32 v132, v132, 0, v144
	v_or_b32_e32 v132, s1, v132
	v_ashrrev_i32_e32 v133, 31, v132
	v_lshlrev_b64 v[132:133], 6, v[132:133]
	v_lshl_add_u64 v[132:133], s[24:25], 0, v[132:133]
	v_lshl_add_u64 v[132:133], v[132:133], 0, v[130:131]
	ds_bpermute_b32 v207, v137, v206
	s_waitcnt vmcnt(2)
	v_mov_b64_e32 v[140:141], v[166:167]
	v_mov_b64_e32 v[142:143], v[168:169]
	v_mov_b32_e32 v132, v141
	v_mov_b32_e32 v133, v142
	v_mov_b32_e32 v141, v143
	v_pk_add_f32 v[132:133], v[132:133], v[140:141]
	s_nop 0
	v_add_f32_e32 v132, v132, v133
	ds_bpermute_b32 v133, v138, v132
	s_waitcnt lgkmcnt(0)
	v_add_f32_e32 v204, v132, v133
	v_add_u32_e32 v132, 0x82, v190
	v_med3_i32 v132, v132, 0, v144
	v_or_b32_e32 v132, s1, v132
	v_ashrrev_i32_e32 v133, 31, v132
	v_lshlrev_b64 v[132:133], 6, v[132:133]
	v_lshl_add_u64 v[132:133], s[24:25], 0, v[132:133]
	v_lshl_add_u64 v[132:133], v[132:133], 0, v[130:131]
	ds_bpermute_b32 v205, v137, v204
	s_waitcnt vmcnt(1)
	v_mov_b64_e32 v[140:141], v[170:171]
	v_mov_b64_e32 v[142:143], v[172:173]
	v_mov_b32_e32 v132, v141
	v_mov_b32_e32 v133, v142
	v_mov_b32_e32 v141, v143
	v_pk_add_f32 v[132:133], v[132:133], v[140:141]
	s_nop 0
	v_add_f32_e32 v132, v132, v133
	ds_bpermute_b32 v133, v138, v132
	s_waitcnt lgkmcnt(0)
	v_add_f32_e32 v132, v132, v133
	ds_bpermute_b32 v133, v137, v132
	s_waitcnt lgkmcnt(0)
	v_add_f32_e32 v132, v132, v133
	v_fmamk_f32 v132, v132, 0x3a800000, v243
	v_cmp_gt_f32_e32 vcc, s37, v132
	v_mul_f32_e32 v133, 0x4f800000, v132
	s_nop 0
	v_cndmask_b32_e32 v132, v132, v133, vcc
	v_sqrt_f32_e32 v133, v132
	s_nop 0
	v_add_u32_e32 v135, -1, v133
	v_fma_f32 v139, -v135, v133, v132
	v_cmp_ge_f32_e64 s[44:45], 0, v139
	v_add_u32_e32 v139, 1, v133
	s_nop 0
	v_cndmask_b32_e64 v135, v133, v135, s[44:45]
	v_fma_f32 v133, -v139, v133, v132
	v_cmp_lt_f32_e64 s[44:45], 0, v133
	s_nop 1
	v_cndmask_b32_e64 v133, v135, v139, s[44:45]
	v_mul_f32_e32 v135, 0x37800000, v133
	v_cndmask_b32_e32 v133, v133, v135, vcc
	v_cmp_class_f32_e32 vcc, v132, v241
	s_nop 1
	v_cndmask_b32_e32 v132, v133, v132, vcc
	v_div_scale_f32 v133, s[10:11], v132, v132, 1.0
	v_rcp_f32_e32 v135, v133
	s_nop 0
	v_fma_f32 v139, -v133, v135, 1.0
	v_fmac_f32_e32 v135, v139, v135
	v_div_scale_f32 v139, vcc, 1.0, v132, 1.0
	v_mul_f32_e32 v140, v139, v135
	v_fma_f32 v141, -v133, v140, v139
	v_fmac_f32_e32 v140, v141, v135
	v_fma_f32 v133, -v133, v140, v139
	v_div_fmas_f32 v133, v133, v135, v140
	v_div_fixup_f32 v132, v133, v132, 1.0
	v_pk_mul_f32 v[108:109], v[108:109], v[132:133] op_sel_hi:[1,0]
	v_pk_mul_f32 v[106:107], v[106:107], v[132:133] op_sel_hi:[1,0]
	v_pk_mul_f32 v[36:37], v[36:37], v[132:133] op_sel_hi:[1,0]
	v_pk_mul_f32 v[34:35], v[34:35], v[132:133] op_sel_hi:[1,0]
	v_pk_mul_f32 v[112:113], v[112:113], v[132:133] op_sel_hi:[1,0]
	v_pk_mul_f32 v[110:111], v[110:111], v[132:133] op_sel_hi:[1,0]
	v_pk_mul_f32 v[40:41], v[40:41], v[132:133] op_sel_hi:[1,0]
	v_pk_mul_f32 v[38:39], v[38:39], v[132:133] op_sel_hi:[1,0]
	v_add_u32_e32 v132, 0x83, v190
	v_med3_i32 v132, v132, 0, v144
	v_or_b32_e32 v132, s1, v132
	v_ashrrev_i32_e32 v133, 31, v132
	v_lshlrev_b64 v[132:133], 6, v[132:133]
	v_lshl_add_u64 v[132:133], s[24:25], 0, v[132:133]
	v_lshl_add_u64 v[130:131], v[132:133], 0, v[130:131]
	s_waitcnt vmcnt(0)
	v_mov_b64_e32 v[130:131], v[174:175]
	v_mov_b64_e32 v[132:133], v[176:177]
	v_mov_b32_e32 v140, v131
	v_mov_b32_e32 v141, v132
	v_mov_b32_e32 v131, v133
	v_pk_add_f32 v[130:131], v[140:141], v[130:131]
	s_nop 0
	v_add_f32_e32 v130, v130, v131
	ds_bpermute_b32 v131, v138, v130
	s_waitcnt lgkmcnt(0)
	v_add_f32_e32 v130, v130, v131
	ds_bpermute_b32 v131, v137, v130
	s_waitcnt lgkmcnt(0)
	v_add_f32_e32 v130, v130, v131
	v_fmamk_f32 v130, v130, 0x3a800000, v243
	v_cmp_gt_f32_e32 vcc, s37, v130
	v_mul_f32_e32 v131, 0x4f800000, v130
	s_nop 0
	v_cndmask_b32_e32 v130, v130, v131, vcc
	v_sqrt_f32_e32 v131, v130
	s_nop 0
	v_add_u32_e32 v132, -1, v131
	v_fma_f32 v133, -v132, v131, v130
	v_cmp_ge_f32_e64 s[44:45], 0, v133
	v_add_u32_e32 v133, 1, v131
	s_nop 0
	v_cndmask_b32_e64 v132, v131, v132, s[44:45]
	v_fma_f32 v131, -v133, v131, v130
	v_cmp_lt_f32_e64 s[44:45], 0, v131
	s_nop 1
	v_cndmask_b32_e64 v131, v132, v133, s[44:45]
	v_mul_f32_e32 v132, 0x37800000, v131
	v_cndmask_b32_e32 v131, v131, v132, vcc
	v_cmp_class_f32_e32 vcc, v130, v241
	s_nop 1
	v_cndmask_b32_e32 v130, v131, v130, vcc
	v_div_scale_f32 v131, s[10:11], v130, v130, 1.0
	v_rcp_f32_e32 v132, v131
	s_nop 0
	v_fma_f32 v133, -v131, v132, 1.0
	v_fmac_f32_e32 v132, v133, v132
	v_div_scale_f32 v133, vcc, 1.0, v130, 1.0
	v_mul_f32_e32 v135, v133, v132
	v_fma_f32 v137, -v131, v135, v133
	v_fmac_f32_e32 v135, v137, v132
	v_fma_f32 v131, -v131, v135, v133
	v_div_fmas_f32 v131, v131, v132, v135
	v_div_fixup_f32 v130, v131, v130, 1.0
	v_pk_mul_f32 v[104:105], v[104:105], v[130:131] op_sel_hi:[1,0]
	v_pk_mul_f32 v[102:103], v[102:103], v[130:131] op_sel_hi:[1,0]
	v_pk_mul_f32 v[76:77], v[76:77], v[130:131] op_sel_hi:[1,0]
	v_pk_mul_f32 v[74:75], v[74:75], v[130:131] op_sel_hi:[1,0]
	v_pk_mul_f32 v[100:101], v[100:101], v[130:131] op_sel_hi:[1,0]
	v_pk_mul_f32 v[98:99], v[98:99], v[130:131] op_sel_hi:[1,0]
	v_pk_mul_f32 v[88:89], v[88:89], v[130:131] op_sel_hi:[1,0]
	v_pk_mul_f32 v[86:87], v[86:87], v[130:131] op_sel_hi:[1,0]
	v_cmp_eq_u32_e32 vcc, 15, v203
	s_and_saveexec_b64 s[10:11], vcc
	s_cbranch_execz .LBB0_936
	v_lshlrev_b32_e32 v130, 4, v136
	v_readlane_b32 s1, v255, 5
	s_nop 1
	v_add_u32_e32 v131, s1, v130
	v_readlane_b32 s1, v255, 6
	ds_write_b128 v131, v[114:117]
	ds_write_b128 v131, v[122:125] offset:1024
	ds_write_b128 v131, v[42:45] offset:64
	ds_write_b128 v131, v[58:61] offset:1088
	ds_write_b128 v131, v[118:121] offset:512
	ds_write_b128 v131, v[126:129] offset:1536
	ds_write_b128 v131, v[54:57] offset:576
	ds_write_b128 v131, v[62:65] offset:1600
	v_add_u32_e32 v130, s1, v130
	ds_write_b128 v130, v[106:109]
	ds_write_b128 v130, v[102:105] offset:1024
	ds_write_b128 v131, v[34:37] offset:4160
	ds_write_b128 v131, v[74:77] offset:5184
	ds_write_b128 v131, v[110:113] offset:4608
	ds_write_b128 v131, v[98:101] offset:5632
	ds_write_b128 v131, v[38:41] offset:4672
	ds_write_b128 v131, v[86:89] offset:5696
